# attention loop: first V-fragment LDS reads issued right after the last QK MFMA (before flag subs and max)
# speedup vs baseline: 1.0339x; 1.0324x over previous
.Lq1_body:
	global_load_dwordx4 v[28:31], v202, s[100:101] offset:-128
	global_load_dwordx4 v[32:35], v202, s[100:101]
	global_load_dwordx4 v[4:7], v203, s[100:101] offset:-128
	global_load_dwordx4 v[12:15], v203, s[100:101]
	ds_read_b128 v[44:47], v214 offset:35840
	ds_read_b128 v[72:75], v214 offset:35904
	ds_read_b128 v[92:95], v214 offset:40192
	ds_read_b128 v[112:115], v214 offset:40256
	ds_read_b128 v[132:135], v214 offset:44544
	ds_read_b128 v[148:151], v214 offset:44608
	ds_read_b128 v[136:139], v214 offset:48896
	ds_read_b128 v[152:155], v214 offset:48960
	s_waitcnt lgkmcnt(7)
	v_mfma_f32_16x16x32_bf16 v[140:143], v[44:47], v[8:11], 0
	v_mfma_f32_16x16x32_bf16 v[44:47], v[44:47], v[20:23], 0
	s_waitcnt lgkmcnt(1)
	v_mfma_f32_16x16x32_bf16 v[156:159], v[92:95], v[8:11], 0
	v_mfma_f32_16x16x32_bf16 v[92:95], v[92:95], v[20:23], 0
	v_mfma_f32_16x16x32_bf16 v[160:163], v[132:135], v[8:11], 0
	v_mfma_f32_16x16x32_bf16 v[132:135], v[132:135], v[20:23], 0
	v_mfma_f32_16x16x32_bf16 v[164:167], v[136:139], v[8:11], 0
	v_mfma_f32_16x16x32_bf16 v[168:171], v[136:139], v[20:23], 0
	v_mfma_f32_16x16x32_bf16 v[144:147], v[72:75], v[16:19], v[140:143]
	v_mfma_f32_16x16x32_bf16 v[136:139], v[72:75], v[24:27], v[44:47]
	v_mfma_f32_16x16x32_bf16 v[44:47], v[112:115], v[16:19], v[156:159]
	v_mfma_f32_16x16x32_bf16 v[92:95], v[112:115], v[24:27], v[92:95]
	v_mfma_f32_16x16x32_bf16 v[140:143], v[148:151], v[16:19], v[160:163]
	v_mfma_f32_16x16x32_bf16 v[132:135], v[148:151], v[24:27], v[132:135]
	s_waitcnt lgkmcnt(0)
	v_mfma_f32_16x16x32_bf16 v[72:75], v[152:155], v[16:19], v[164:167]
	v_mfma_f32_16x16x32_bf16 v[112:115], v[152:155], v[24:27], v[168:171]
	ds_read_b64_tr_b16 v[148:149], v215 offset:17408
	ds_read_b64_tr_b16 v[152:153], v215 offset:17440
	ds_read_b64_tr_b16 v[156:157], v215 offset:17472
	ds_read_b64_tr_b16 v[160:161], v215 offset:17504
	ds_read_b64_tr_b16 v[150:151], v215 offset:22016
	ds_read_b64_tr_b16 v[154:155], v215 offset:22048
	ds_read_b64_tr_b16 v[158:159], v215 offset:22080
	ds_read_b64_tr_b16 v[162:163], v215 offset:22112
	s_cmp_eq_u32 s98, 0
	s_cbranch_scc1 .LBB0_859
	v_sub_f32_e32 v147, v147, v196
	v_sub_f32_e32 v146, v146, v196
	v_sub_f32_e32 v145, v145, v196
	v_sub_f32_e32 v144, v144, v196
	v_sub_f32_e32 v47, v47, v196
	v_sub_f32_e32 v46, v46, v196
	v_sub_f32_e32 v45, v45, v196
	v_sub_f32_e32 v44, v44, v196
	v_sub_f32_e32 v143, v143, v196
	v_sub_f32_e32 v142, v142, v196
	v_sub_f32_e32 v141, v141, v196
	v_sub_f32_e32 v140, v140, v196
	v_sub_f32_e32 v75, v75, v196
	v_sub_f32_e32 v74, v74, v196
	v_sub_f32_e32 v73, v73, v196
	v_sub_f32_e32 v72, v72, v196
	v_sub_f32_e32 v139, v139, v197
	v_sub_f32_e32 v138, v138, v197
	v_sub_f32_e32 v137, v137, v197
	v_sub_f32_e32 v136, v136, v197
	v_sub_f32_e32 v95, v95, v197
	v_sub_f32_e32 v94, v94, v197
	v_sub_f32_e32 v93, v93, v197
	v_sub_f32_e32 v92, v92, v197
	v_sub_f32_e32 v135, v135, v197
	v_sub_f32_e32 v134, v134, v197
	v_sub_f32_e32 v133, v133, v197
	v_sub_f32_e32 v132, v132, v197
	v_sub_f32_e32 v115, v115, v197
	v_sub_f32_e32 v114, v114, v197
	v_sub_f32_e32 v113, v113, v197
	v_sub_f32_e32 v112, v112, v197
.LBB0_859:
	s_cmp_le_u32 s87, s86
	s_cbranch_scc1 .LBB0_861
	s_waitcnt lgkmcnt(0)
	v_add_u32_e32 v0, s87, v217
	v_add_u32_e32 v154, 0x80, v0
	v_max_i32_e32 v3, -1, v154
	v_max_i32_e32 v148, -2, v154
	v_max_i32_e32 v149, -3, v154
	v_max_i32_e32 v150, -16, v154
	v_max_i32_e32 v151, 0xffffffef, v154
	v_max_i32_e32 v152, 0xffffffee, v154
	v_max_i32_e32 v153, 0xffffffed, v154
	v_add_u32_e32 v3, 1, v3
	v_add_u32_e32 v148, 2, v148
	v_add_u32_e32 v149, 3, v149
	v_add_u32_e32 v150, 16, v150
	v_add_u32_e32 v151, 17, v151
	v_add_u32_e32 v152, 18, v152
	v_add_u32_e32 v153, 19, v153
	v_med3_i32 v2, v154, 0, v209
	v_min_u32_e32 v3, 0xff, v3
	v_min_u32_e32 v148, 0xff, v148
	v_min_u32_e32 v149, 0xff, v149
	v_min_u32_e32 v150, 0xff, v150
	v_min_u32_e32 v151, 0xff, v151
	v_min_u32_e32 v152, 0xff, v152
	v_min_u32_e32 v153, 0xff, v153
	v_lshl_add_u32 v2, v2, 2, s71
	v_lshl_add_u32 v3, v3, 2, s71
	v_lshl_add_u32 v148, v148, 2, s71
	v_lshl_add_u32 v149, v149, 2, s71
	v_lshl_add_u32 v150, v150, 2, s71
	v_lshl_add_u32 v151, v151, 2, s71
	v_lshl_add_u32 v152, v152, 2, s71
	v_lshl_add_u32 v153, v153, 2, s71
	ds_read_b32 v2, v2
	ds_read_b32 v3, v3
	ds_read_b32 v148, v148
	ds_read_b32 v149, v149
	ds_read_b32 v150, v150
	ds_read_b32 v151, v151
	ds_read_b32 v152, v152
	ds_read_b32 v153, v153
	s_waitcnt lgkmcnt(4)
	v_pk_add_f32 v[146:147], v[146:147], v[148:149]
	v_pk_add_f32 v[144:145], v[144:145], v[2:3]
	v_max_i32_e32 v2, 0xffffffe0, v154
	v_max_i32_e32 v3, 0xffffffdf, v154
	v_max_i32_e32 v148, 0xffffffde, v154
	v_max_i32_e32 v149, 0xffffffdd, v154
	v_max_i32_e32 v155, 0xffffffd0, v154
	v_max_i32_e32 v156, 0xffffffcf, v154
	v_max_i32_e32 v157, 0xffffffce, v154
	v_add_u32_e32 v2, 32, v2
	v_add_u32_e32 v3, 33, v3
	v_add_u32_e32 v148, 34, v148
	v_add_u32_e32 v149, 35, v149
	v_add_u32_e32 v155, 48, v155
	v_add_u32_e32 v156, 49, v156
	v_add_u32_e32 v157, 50, v157
	v_max_i32_e32 v154, 0xffffffcd, v154
	v_min_u32_e32 v2, 0xff, v2
	v_min_u32_e32 v3, 0xff, v3
	v_min_u32_e32 v148, 0xff, v148
	v_min_u32_e32 v149, 0xff, v149
	v_min_u32_e32 v155, 0xff, v155
	v_min_u32_e32 v156, 0xff, v156
	v_min_u32_e32 v157, 0xff, v157
	v_add_u32_e32 v154, 51, v154
	v_lshl_add_u32 v2, v2, 2, s71
	v_lshl_add_u32 v3, v3, 2, s71
	v_lshl_add_u32 v148, v148, 2, s71
	v_lshl_add_u32 v149, v149, 2, s71
	v_lshl_add_u32 v155, v155, 2, s71
	v_lshl_add_u32 v156, v156, 2, s71
	v_lshl_add_u32 v157, v157, 2, s71
	v_min_u32_e32 v154, 0xff, v154
	v_lshl_add_u32 v158, v154, 2, s71
	ds_read_b32 v2, v2
	ds_read_b32 v3, v3
	ds_read_b32 v148, v148
	ds_read_b32 v149, v149
	ds_read_b32 v154, v155
	ds_read_b32 v155, v156
	ds_read_b32 v156, v157
	ds_read_b32 v157, v158
	v_add_u32_e32 v0, 0x70, v0
	s_waitcnt lgkmcnt(8)
	v_pk_add_f32 v[46:47], v[46:47], v[152:153]
	v_pk_add_f32 v[44:45], v[44:45], v[150:151]
	s_waitcnt lgkmcnt(4)
	v_pk_add_f32 v[142:143], v[142:143], v[148:149]
	v_pk_add_f32 v[140:141], v[140:141], v[2:3]
	v_max_i32_e32 v3, -1, v0
	v_max_i32_e32 v148, -2, v0
	v_max_i32_e32 v149, -3, v0
	v_max_i32_e32 v150, -16, v0
	v_max_i32_e32 v151, 0xffffffef, v0
	v_max_i32_e32 v152, 0xffffffee, v0
	v_max_i32_e32 v153, 0xffffffed, v0
	v_add_u32_e32 v3, 1, v3
	v_add_u32_e32 v148, 2, v148
	v_add_u32_e32 v149, 3, v149
	v_add_u32_e32 v150, 16, v150
	v_add_u32_e32 v151, 17, v151
	v_add_u32_e32 v152, 18, v152
	v_add_u32_e32 v153, 19, v153
	v_med3_i32 v2, v0, 0, v209
	v_min_u32_e32 v3, 0xff, v3
	v_min_u32_e32 v148, 0xff, v148
	v_min_u32_e32 v149, 0xff, v149
	v_min_u32_e32 v150, 0xff, v150
	v_min_u32_e32 v151, 0xff, v151
	v_min_u32_e32 v152, 0xff, v152
	v_min_u32_e32 v153, 0xff, v153
	v_lshl_add_u32 v2, v2, 2, s71
	v_lshl_add_u32 v3, v3, 2, s71
	v_lshl_add_u32 v148, v148, 2, s71
	v_lshl_add_u32 v149, v149, 2, s71
	v_lshl_add_u32 v150, v150, 2, s71
	v_lshl_add_u32 v151, v151, 2, s71
	v_lshl_add_u32 v152, v152, 2, s71
	v_lshl_add_u32 v153, v153, 2, s71
	ds_read_b32 v2, v2
	ds_read_b32 v3, v3
	ds_read_b32 v148, v148
	ds_read_b32 v149, v149
	ds_read_b32 v150, v150
	ds_read_b32 v151, v151
	ds_read_b32 v152, v152
	ds_read_b32 v153, v153
	s_waitcnt lgkmcnt(8)
	v_pk_add_f32 v[74:75], v[74:75], v[156:157]
	v_pk_add_f32 v[72:73], v[72:73], v[154:155]
	s_waitcnt lgkmcnt(4)
	v_pk_add_f32 v[138:139], v[138:139], v[148:149]
	v_pk_add_f32 v[136:137], v[136:137], v[2:3]
	v_max_i32_e32 v2, 0xffffffe0, v0
	v_max_i32_e32 v3, 0xffffffdf, v0
	v_max_i32_e32 v148, 0xffffffde, v0
	v_max_i32_e32 v149, 0xffffffdd, v0
	v_max_i32_e32 v154, 0xffffffd0, v0
	v_max_i32_e32 v155, 0xffffffcf, v0
	v_max_i32_e32 v156, 0xffffffce, v0
	v_add_u32_e32 v2, 32, v2
	v_add_u32_e32 v3, 33, v3
	v_add_u32_e32 v148, 34, v148
	v_add_u32_e32 v149, 35, v149
	v_add_u32_e32 v154, 48, v154
	v_add_u32_e32 v155, 49, v155
	v_add_u32_e32 v156, 50, v156
	v_max_i32_e32 v0, 0xffffffcd, v0
	v_min_u32_e32 v2, 0xff, v2
	v_min_u32_e32 v3, 0xff, v3
	v_min_u32_e32 v148, 0xff, v148
	v_min_u32_e32 v149, 0xff, v149
	v_min_u32_e32 v154, 0xff, v154
	v_min_u32_e32 v155, 0xff, v155
	v_min_u32_e32 v156, 0xff, v156
	v_add_u32_e32 v0, 51, v0
	v_lshl_add_u32 v2, v2, 2, s71
	v_lshl_add_u32 v3, v3, 2, s71
	v_lshl_add_u32 v148, v148, 2, s71
	v_lshl_add_u32 v149, v149, 2, s71
	v_lshl_add_u32 v154, v154, 2, s71
	v_lshl_add_u32 v155, v155, 2, s71
	v_lshl_add_u32 v156, v156, 2, s71
	v_min_u32_e32 v0, 0xff, v0
	v_lshl_add_u32 v0, v0, 2, s71
	ds_read_b32 v2, v2
	ds_read_b32 v3, v3
	ds_read_b32 v148, v148
	ds_read_b32 v149, v149
	ds_read_b32 v154, v154
	ds_read_b32 v155, v155
	ds_read_b32 v156, v156
	ds_read_b32 v157, v0
	s_waitcnt lgkmcnt(8)
	v_pk_add_f32 v[94:95], v[94:95], v[152:153]
	v_pk_add_f32 v[92:93], v[92:93], v[150:151]
	s_waitcnt lgkmcnt(4)
	v_pk_add_f32 v[134:135], v[134:135], v[148:149]
	v_pk_add_f32 v[132:133], v[132:133], v[2:3]
	s_waitcnt lgkmcnt(0)
	v_pk_add_f32 v[114:115], v[114:115], v[156:157]
	v_pk_add_f32 v[112:113], v[112:113], v[154:155]
	ds_read_b64_tr_b16 v[148:149], v215 offset:17408
	ds_read_b64_tr_b16 v[152:153], v215 offset:17440
	ds_read_b64_tr_b16 v[156:157], v215 offset:17472
	ds_read_b64_tr_b16 v[160:161], v215 offset:17504
	ds_read_b64_tr_b16 v[150:151], v215 offset:22016
	ds_read_b64_tr_b16 v[154:155], v215 offset:22048
	ds_read_b64_tr_b16 v[158:159], v215 offset:22080
	ds_read_b64_tr_b16 v[162:163], v215 offset:22112
.LBB0_861:
	v_max_f32_e32 v0, v144, v145
	v_max3_f32 v2, v147, v44, v45
	v_max3_f32 v0, v0, v146, v46
	v_max3_f32 v2, v2, v140, v141
	v_max3_f32 v0, v0, v47, v142
	v_max3_f32 v2, v2, v72, v73
	v_max3_f32 v0, v0, v143, v74
	v_max3_f32 v0, v0, v75, v2
	v_max_f32_e32 v2, v136, v137
	v_max3_f32 v3, v139, v92, v93
	v_max3_f32 v2, v2, v138, v94
	v_max3_f32 v3, v3, v132, v133
	v_max3_f32 v2, v2, v95, v134
	v_max3_f32 v3, v3, v112, v113
	v_max3_f32 v2, v2, v135, v114
	v_max3_f32 v2, v2, v115, v3
	v_max_f32_e32 v3, v0, v2
	v_cmp_lt_f32_e32 vcc, s74, v3
	s_cmp_lg_u64 vcc, 0
	s_cselect_b64 s[0:1], -1, 0
	s_cbranch_vccz .LBB0_863
	s_waitcnt lgkmcnt(0)
	s_mov_b32 s98, 1
	v_and_b32_e32 v148, 64, v212
	v_xor_b32_e32 v3, 16, v212
	v_add_u32_e32 v148, 64, v148
	v_cmp_lt_i32_e32 vcc, v3, v148
	v_xor_b32_e32 v149, 32, v212
	s_nop 0
	v_cndmask_b32_e32 v3, v212, v3, vcc
	v_lshlrev_b32_e32 v3, 2, v3
	ds_bpermute_b32 v150, v3, v0
	ds_bpermute_b32 v3, v3, v2
	v_cmp_lt_i32_e32 vcc, v149, v148
	v_max_f32_e32 v2, v2, v2
	v_max_f32_e32 v0, v0, v0
	v_cndmask_b32_e32 v148, v212, v149, vcc
	s_waitcnt lgkmcnt(0)
	v_max_f32_e32 v3, v3, v3
	v_lshlrev_b32_e32 v148, 2, v148
	v_max_f32_e32 v149, v150, v150
	v_max_f32_e32 v2, v2, v3
	v_max_f32_e32 v0, v0, v149
	ds_bpermute_b32 v3, v148, v2
	ds_bpermute_b32 v149, v148, v0
	s_waitcnt lgkmcnt(1)
	v_max_f32_e32 v3, v3, v3
	s_waitcnt lgkmcnt(0)
	v_max_f32_e32 v148, v149, v149
	v_max_f32_e32 v2, v2, v3
	v_max_f32_e32 v0, v0, v148
	v_cmp_lt_f32_e32 vcc, s74, v2
	s_nop 1
	v_cndmask_b32_e32 v3, 0, v2, vcc
	v_cmp_lt_f32_e32 vcc, s74, v0
	v_exp_f32_e64 v201, -v3
	v_sub_f32_e32 v136, v136, v3
	v_cndmask_b32_e32 v2, 0, v0, vcc
	v_exp_f32_e64 v200, -v2
	v_sub_f32_e32 v144, v144, v2
	v_sub_f32_e32 v145, v145, v2
	v_sub_f32_e32 v146, v146, v2
	v_sub_f32_e32 v147, v147, v2
	v_sub_f32_e32 v44, v44, v2
	v_sub_f32_e32 v45, v45, v2
	v_sub_f32_e32 v46, v46, v2
	v_sub_f32_e32 v47, v47, v2
	v_sub_f32_e32 v140, v140, v2
	v_sub_f32_e32 v141, v141, v2
	v_sub_f32_e32 v142, v142, v2
	v_sub_f32_e32 v143, v143, v2
	v_sub_f32_e32 v72, v72, v2
	v_sub_f32_e32 v73, v73, v2
	v_sub_f32_e32 v74, v74, v2
	v_sub_f32_e32 v75, v75, v2
	v_pk_add_f32 v[196:197], v[196:197], v[2:3]
	v_sub_f32_e32 v137, v137, v3
	v_sub_f32_e32 v138, v138, v3
	v_sub_f32_e32 v139, v139, v3
	v_sub_f32_e32 v92, v92, v3
	v_sub_f32_e32 v93, v93, v3
	v_sub_f32_e32 v94, v94, v3
	v_sub_f32_e32 v95, v95, v3
	v_sub_f32_e32 v132, v132, v3
	v_sub_f32_e32 v133, v133, v3
	v_sub_f32_e32 v134, v134, v3
	v_sub_f32_e32 v135, v135, v3
	v_sub_f32_e32 v112, v112, v3
	v_sub_f32_e32 v113, v113, v3
	v_sub_f32_e32 v114, v114, v3
	v_sub_f32_e32 v115, v115, v3
	v_pk_mul_f32 v[198:199], v[198:199], v[200:201]
	ds_read_b64_tr_b16 v[148:149], v215 offset:17408
	ds_read_b64_tr_b16 v[152:153], v215 offset:17440
	ds_read_b64_tr_b16 v[156:157], v215 offset:17472
	ds_read_b64_tr_b16 v[160:161], v215 offset:17504
	ds_read_b64_tr_b16 v[150:151], v215 offset:22016
	ds_read_b64_tr_b16 v[154:155], v215 offset:22048
	ds_read_b64_tr_b16 v[158:159], v215 offset:22080
	ds_read_b64_tr_b16 v[162:163], v215 offset:22112

.Lq1_h2_nok:
	global_load_dwordx4 v[4:7], v203, s[100:101] offset:-128
	global_load_dwordx4 v[12:15], v203, s[100:101]
	s_cmp_ge_u32 s89, s83
	s_cbranch_scc1 .Lq1_h2_pvonly
	ds_read_b128 v[36:39], v214
	ds_read_b128 v[40:43], v214 offset:64
	ds_read_b128 v[60:63], v214 offset:4352
	ds_read_b128 v[84:87], v214 offset:4416
	ds_read_b128 v[64:67], v214 offset:8704
	ds_read_b128 v[124:127], v214 offset:8768
	ds_read_b128 v[108:111], v214 offset:13056
	ds_read_b128 v[100:103], v214 offset:13120
	s_waitcnt lgkmcnt(7)
	v_mfma_f32_16x16x32_bf16 v[120:123], v[36:39], v[8:11], 0
	v_mfma_f32_16x16x32_bf16 v[36:39], v[36:39], v[20:23], 0
	s_waitcnt lgkmcnt(1)
	v_mfma_f32_16x16x32_bf16 v[116:119], v[60:63], v[8:11], 0
	v_mfma_f32_16x16x32_bf16 v[60:63], v[60:63], v[20:23], 0
	v_mfma_f32_16x16x32_bf16 v[96:99], v[64:67], v[8:11], 0
	v_mfma_f32_16x16x32_bf16 v[64:67], v[64:67], v[20:23], 0
	v_mfma_f32_16x16x32_bf16 v[104:107], v[108:111], v[8:11], 0
	v_mfma_f32_16x16x32_bf16 v[76:79], v[108:111], v[20:23], 0
	v_mfma_f32_16x16x32_bf16 v[128:131], v[40:43], v[16:19], v[120:123]
	v_mfma_f32_16x16x32_bf16 v[108:111], v[40:43], v[24:27], v[36:39]
	v_mfma_f32_16x16x32_bf16 v[36:39], v[84:87], v[16:19], v[116:119]
	v_mfma_f32_16x16x32_bf16 v[60:63], v[84:87], v[24:27], v[60:63]
	v_mfma_f32_16x16x32_bf16 v[120:123], v[124:127], v[16:19], v[96:99]
	v_mfma_f32_16x16x32_bf16 v[64:67], v[124:127], v[24:27], v[64:67]
	s_waitcnt lgkmcnt(0)
	v_mfma_f32_16x16x32_bf16 v[40:43], v[100:103], v[16:19], v[104:107]
	v_mfma_f32_16x16x32_bf16 v[84:87], v[100:103], v[24:27], v[76:79]
	ds_read_b64_tr_b16 v[124:125], v215 offset:53248
	ds_read_b64_tr_b16 v[100:101], v215 offset:53280
	ds_read_b64_tr_b16 v[116:117], v215 offset:53312
	ds_read_b64_tr_b16 v[96:97], v215 offset:53344
	ds_read_b64_tr_b16 v[126:127], v215 offset:57856
	ds_read_b64_tr_b16 v[102:103], v215 offset:57888
	ds_read_b64_tr_b16 v[118:119], v215 offset:57920
	ds_read_b64_tr_b16 v[98:99], v215 offset:57952
	s_cmp_eq_u32 s98, 0
	s_cbranch_scc1 .LBB0_875
	v_sub_f32_e32 v131, v131, v196
	v_sub_f32_e32 v130, v130, v196
	v_sub_f32_e32 v129, v129, v196
	v_sub_f32_e32 v128, v128, v196
	v_sub_f32_e32 v39, v39, v196
	v_sub_f32_e32 v38, v38, v196
	v_sub_f32_e32 v37, v37, v196
	v_sub_f32_e32 v36, v36, v196
	v_sub_f32_e32 v123, v123, v196
	v_sub_f32_e32 v122, v122, v196
	v_sub_f32_e32 v121, v121, v196
	v_sub_f32_e32 v120, v120, v196
	v_sub_f32_e32 v43, v43, v196
	v_sub_f32_e32 v42, v42, v196
	v_sub_f32_e32 v41, v41, v196
	v_sub_f32_e32 v40, v40, v196
	v_sub_f32_e32 v111, v111, v197
	v_sub_f32_e32 v110, v110, v197
	v_sub_f32_e32 v109, v109, v197
	v_sub_f32_e32 v108, v108, v197
	v_sub_f32_e32 v63, v63, v197
	v_sub_f32_e32 v62, v62, v197
	v_sub_f32_e32 v61, v61, v197
	v_sub_f32_e32 v60, v60, v197
	v_sub_f32_e32 v67, v67, v197
	v_sub_f32_e32 v66, v66, v197
	v_sub_f32_e32 v65, v65, v197
	v_sub_f32_e32 v64, v64, v197
	v_sub_f32_e32 v87, v87, v197
	v_sub_f32_e32 v86, v86, v197
	v_sub_f32_e32 v85, v85, v197
	v_sub_f32_e32 v84, v84, v197
.LBB0_875:
	s_add_i32 s2, s87, 64
	s_cmp_le_u32 s2, s86
	s_cbranch_scc1 .LBB0_877
	s_waitcnt lgkmcnt(0)
	v_add_u32_e32 v0, s87, v217
	v_add_u32_e32 v102, 0xc0, v0
	v_max_i32_e32 v3, -1, v102
	v_max_i32_e32 v124, -2, v102
	v_max_i32_e32 v125, -3, v102
	v_max_i32_e32 v126, -16, v102
	v_max_i32_e32 v127, 0xffffffef, v102
	v_max_i32_e32 v100, 0xffffffee, v102
	v_max_i32_e32 v101, 0xffffffed, v102
	v_add_u32_e32 v3, 1, v3
	v_add_u32_e32 v124, 2, v124
	v_add_u32_e32 v125, 3, v125
	v_add_u32_e32 v126, 16, v126
	v_add_u32_e32 v127, 17, v127
	v_add_u32_e32 v100, 18, v100
	v_add_u32_e32 v101, 19, v101
	v_med3_i32 v2, v102, 0, v209
	v_min_u32_e32 v3, 0xff, v3
	v_min_u32_e32 v124, 0xff, v124
	v_min_u32_e32 v125, 0xff, v125
	v_min_u32_e32 v126, 0xff, v126
	v_min_u32_e32 v127, 0xff, v127
	v_min_u32_e32 v100, 0xff, v100
	v_min_u32_e32 v101, 0xff, v101
	v_lshl_add_u32 v2, v2, 2, s71
	v_lshl_add_u32 v3, v3, 2, s71
	v_lshl_add_u32 v124, v124, 2, s71
	v_lshl_add_u32 v125, v125, 2, s71
	v_lshl_add_u32 v126, v126, 2, s71
	v_lshl_add_u32 v127, v127, 2, s71
	v_lshl_add_u32 v100, v100, 2, s71
	v_lshl_add_u32 v101, v101, 2, s71
	ds_read_b32 v2, v2
	ds_read_b32 v3, v3
	ds_read_b32 v124, v124
	ds_read_b32 v125, v125
	ds_read_b32 v126, v126
	ds_read_b32 v127, v127
	ds_read_b32 v100, v100
	ds_read_b32 v101, v101
	s_waitcnt lgkmcnt(4)
	v_pk_add_f32 v[130:131], v[130:131], v[124:125]
	v_pk_add_f32 v[128:129], v[128:129], v[2:3]
	v_max_i32_e32 v2, 0xffffffe0, v102
	v_max_i32_e32 v3, 0xffffffdf, v102
	v_max_i32_e32 v124, 0xffffffde, v102
	v_max_i32_e32 v125, 0xffffffdd, v102
	v_max_i32_e32 v103, 0xffffffd0, v102
	v_max_i32_e32 v116, 0xffffffcf, v102
	v_max_i32_e32 v117, 0xffffffce, v102
	v_add_u32_e32 v2, 32, v2
	v_add_u32_e32 v3, 33, v3
	v_add_u32_e32 v124, 34, v124
	v_add_u32_e32 v125, 35, v125
	v_add_u32_e32 v103, 48, v103
	v_add_u32_e32 v116, 49, v116
	v_add_u32_e32 v117, 50, v117
	v_max_i32_e32 v102, 0xffffffcd, v102
	v_min_u32_e32 v2, 0xff, v2
	v_min_u32_e32 v3, 0xff, v3
	v_min_u32_e32 v124, 0xff, v124
	v_min_u32_e32 v125, 0xff, v125
	v_min_u32_e32 v103, 0xff, v103
	v_min_u32_e32 v116, 0xff, v116
	v_min_u32_e32 v117, 0xff, v117
	v_add_u32_e32 v102, 51, v102
	v_lshl_add_u32 v2, v2, 2, s71
	v_lshl_add_u32 v3, v3, 2, s71
	v_lshl_add_u32 v124, v124, 2, s71
	v_lshl_add_u32 v125, v125, 2, s71
	v_lshl_add_u32 v103, v103, 2, s71
	v_lshl_add_u32 v116, v116, 2, s71
	v_lshl_add_u32 v117, v117, 2, s71
	v_min_u32_e32 v102, 0xff, v102
	v_lshl_add_u32 v118, v102, 2, s71
	ds_read_b32 v2, v2
	ds_read_b32 v3, v3
	ds_read_b32 v124, v124
	ds_read_b32 v125, v125
	ds_read_b32 v102, v103
	ds_read_b32 v103, v116
	ds_read_b32 v116, v117
	ds_read_b32 v117, v118
	v_add_u32_e32 v0, 0xb0, v0
	s_waitcnt lgkmcnt(8)
	v_pk_add_f32 v[38:39], v[38:39], v[100:101]
	v_pk_add_f32 v[36:37], v[36:37], v[126:127]
	s_waitcnt lgkmcnt(4)
	v_pk_add_f32 v[122:123], v[122:123], v[124:125]
	v_pk_add_f32 v[120:121], v[120:121], v[2:3]
	v_max_i32_e32 v3, -1, v0
	v_max_i32_e32 v124, -2, v0
	v_max_i32_e32 v125, -3, v0
	v_max_i32_e32 v126, -16, v0
	v_max_i32_e32 v127, 0xffffffef, v0
	v_max_i32_e32 v100, 0xffffffee, v0
	v_max_i32_e32 v101, 0xffffffed, v0
	v_add_u32_e32 v3, 1, v3
	v_add_u32_e32 v124, 2, v124
	v_add_u32_e32 v125, 3, v125
	v_add_u32_e32 v126, 16, v126
	v_add_u32_e32 v127, 17, v127
	v_add_u32_e32 v100, 18, v100
	v_add_u32_e32 v101, 19, v101
	v_med3_i32 v2, v0, 0, v209
	v_min_u32_e32 v3, 0xff, v3
	v_min_u32_e32 v124, 0xff, v124
	v_min_u32_e32 v125, 0xff, v125
	v_min_u32_e32 v126, 0xff, v126
	v_min_u32_e32 v127, 0xff, v127
	v_min_u32_e32 v100, 0xff, v100
	v_min_u32_e32 v101, 0xff, v101
	v_lshl_add_u32 v2, v2, 2, s71
	v_lshl_add_u32 v3, v3, 2, s71
	v_lshl_add_u32 v124, v124, 2, s71
	v_lshl_add_u32 v125, v125, 2, s71
	v_lshl_add_u32 v126, v126, 2, s71
	v_lshl_add_u32 v127, v127, 2, s71
	v_lshl_add_u32 v100, v100, 2, s71
	v_lshl_add_u32 v101, v101, 2, s71
	ds_read_b32 v2, v2
	ds_read_b32 v3, v3
	ds_read_b32 v124, v124
	ds_read_b32 v125, v125
	ds_read_b32 v126, v126
	ds_read_b32 v127, v127
	ds_read_b32 v100, v100
	ds_read_b32 v101, v101
	s_waitcnt lgkmcnt(8)
	v_pk_add_f32 v[42:43], v[42:43], v[116:117]
	v_pk_add_f32 v[40:41], v[40:41], v[102:103]
	s_waitcnt lgkmcnt(4)
	v_pk_add_f32 v[110:111], v[110:111], v[124:125]
	v_pk_add_f32 v[108:109], v[108:109], v[2:3]
	v_max_i32_e32 v2, 0xffffffe0, v0
	v_max_i32_e32 v3, 0xffffffdf, v0
	v_max_i32_e32 v124, 0xffffffde, v0
	v_max_i32_e32 v125, 0xffffffdd, v0
	v_max_i32_e32 v102, 0xffffffd0, v0
	v_max_i32_e32 v103, 0xffffffcf, v0
	v_max_i32_e32 v116, 0xffffffce, v0
	v_add_u32_e32 v2, 32, v2
	v_add_u32_e32 v3, 33, v3
	v_add_u32_e32 v124, 34, v124
	v_add_u32_e32 v125, 35, v125
	v_add_u32_e32 v102, 48, v102
	v_add_u32_e32 v103, 49, v103
	v_add_u32_e32 v116, 50, v116
	v_max_i32_e32 v0, 0xffffffcd, v0
	v_min_u32_e32 v2, 0xff, v2
	v_min_u32_e32 v3, 0xff, v3
	v_min_u32_e32 v124, 0xff, v124
	v_min_u32_e32 v125, 0xff, v125
	v_min_u32_e32 v102, 0xff, v102
	v_min_u32_e32 v103, 0xff, v103
	v_min_u32_e32 v116, 0xff, v116
	v_add_u32_e32 v0, 51, v0
	v_lshl_add_u32 v2, v2, 2, s71
	v_lshl_add_u32 v3, v3, 2, s71
	v_lshl_add_u32 v124, v124, 2, s71
	v_lshl_add_u32 v125, v125, 2, s71
	v_lshl_add_u32 v102, v102, 2, s71
	v_lshl_add_u32 v103, v103, 2, s71
	v_lshl_add_u32 v116, v116, 2, s71
	v_min_u32_e32 v0, 0xff, v0
	v_lshl_add_u32 v0, v0, 2, s71
	ds_read_b32 v2, v2
	ds_read_b32 v3, v3
	ds_read_b32 v124, v124
	ds_read_b32 v125, v125
	ds_read_b32 v102, v102
	ds_read_b32 v103, v103
	ds_read_b32 v116, v116
	ds_read_b32 v117, v0
	s_waitcnt lgkmcnt(8)
	v_pk_add_f32 v[62:63], v[62:63], v[100:101]
	v_pk_add_f32 v[60:61], v[60:61], v[126:127]
	s_waitcnt lgkmcnt(4)
	v_pk_add_f32 v[66:67], v[66:67], v[124:125]
	v_pk_add_f32 v[64:65], v[64:65], v[2:3]
	s_waitcnt lgkmcnt(0)
	v_pk_add_f32 v[86:87], v[86:87], v[116:117]
	v_pk_add_f32 v[84:85], v[84:85], v[102:103]
	ds_read_b64_tr_b16 v[124:125], v215 offset:53248
	ds_read_b64_tr_b16 v[100:101], v215 offset:53280
	ds_read_b64_tr_b16 v[116:117], v215 offset:53312
	ds_read_b64_tr_b16 v[96:97], v215 offset:53344
	ds_read_b64_tr_b16 v[126:127], v215 offset:57856
	ds_read_b64_tr_b16 v[102:103], v215 offset:57888
	ds_read_b64_tr_b16 v[118:119], v215 offset:57920
	ds_read_b64_tr_b16 v[98:99], v215 offset:57952
.LBB0_877:
	v_max_f32_e32 v0, v128, v129
	v_max3_f32 v2, v131, v36, v37
	v_max3_f32 v0, v0, v130, v38
	v_max3_f32 v2, v2, v120, v121
	v_max3_f32 v0, v0, v39, v122
	v_max3_f32 v2, v2, v40, v41
	v_max3_f32 v0, v0, v123, v42
	v_max3_f32 v0, v0, v43, v2
	v_max_f32_e32 v2, v108, v109
	v_max3_f32 v3, v111, v60, v61
	v_max3_f32 v2, v2, v110, v62
	v_max3_f32 v3, v3, v64, v65
	v_max3_f32 v2, v2, v63, v66
	v_max3_f32 v3, v3, v84, v85
	v_max3_f32 v2, v2, v67, v86
	v_max3_f32 v2, v2, v87, v3
	v_max_f32_e32 v3, v0, v2
	v_cmp_lt_f32_e32 vcc, s74, v3
	s_cmp_lg_u64 vcc, 0
	s_cselect_b64 s[2:3], -1, 0
	s_cbranch_vccz .LBB0_879
	s_waitcnt lgkmcnt(0)
	s_mov_b32 s98, 1
	v_and_b32_e32 v124, 64, v212
	v_xor_b32_e32 v3, 16, v212
	v_add_u32_e32 v124, 64, v124
	v_cmp_lt_i32_e32 vcc, v3, v124
	v_xor_b32_e32 v125, 32, v212
	s_nop 0
	v_cndmask_b32_e32 v3, v212, v3, vcc
	v_lshlrev_b32_e32 v3, 2, v3
	ds_bpermute_b32 v126, v3, v0
	ds_bpermute_b32 v3, v3, v2
	v_cmp_lt_i32_e32 vcc, v125, v124
	v_max_f32_e32 v2, v2, v2
	v_max_f32_e32 v0, v0, v0
	v_cndmask_b32_e32 v124, v212, v125, vcc
	s_waitcnt lgkmcnt(0)
	v_max_f32_e32 v3, v3, v3
	v_lshlrev_b32_e32 v124, 2, v124
	v_max_f32_e32 v125, v126, v126
	v_max_f32_e32 v2, v2, v3
	v_max_f32_e32 v0, v0, v125
	ds_bpermute_b32 v3, v124, v2
	ds_bpermute_b32 v125, v124, v0
	s_waitcnt lgkmcnt(1)
	v_max_f32_e32 v3, v3, v3
	s_waitcnt lgkmcnt(0)
	v_max_f32_e32 v124, v125, v125
	v_max_f32_e32 v2, v2, v3
	v_max_f32_e32 v0, v0, v124
	v_cmp_lt_f32_e32 vcc, s74, v2
	s_nop 1
	v_cndmask_b32_e32 v3, 0, v2, vcc
	v_cmp_lt_f32_e32 vcc, s74, v0
	v_exp_f32_e64 v201, -v3
	v_sub_f32_e32 v108, v108, v3
	v_cndmask_b32_e32 v2, 0, v0, vcc
	v_exp_f32_e64 v200, -v2
	v_sub_f32_e32 v128, v128, v2
	v_sub_f32_e32 v129, v129, v2
	v_sub_f32_e32 v130, v130, v2
	v_sub_f32_e32 v131, v131, v2
	v_sub_f32_e32 v36, v36, v2
	v_sub_f32_e32 v37, v37, v2
	v_sub_f32_e32 v38, v38, v2
	v_sub_f32_e32 v39, v39, v2
	v_sub_f32_e32 v120, v120, v2
	v_sub_f32_e32 v121, v121, v2
	v_sub_f32_e32 v122, v122, v2
	v_sub_f32_e32 v123, v123, v2
	v_sub_f32_e32 v40, v40, v2
	v_sub_f32_e32 v41, v41, v2
	v_sub_f32_e32 v42, v42, v2
	v_sub_f32_e32 v43, v43, v2
	v_pk_add_f32 v[196:197], v[196:197], v[2:3]
	v_sub_f32_e32 v109, v109, v3
	v_sub_f32_e32 v110, v110, v3
	v_sub_f32_e32 v111, v111, v3
	v_sub_f32_e32 v60, v60, v3
	v_sub_f32_e32 v61, v61, v3
	v_sub_f32_e32 v62, v62, v3
	v_sub_f32_e32 v63, v63, v3
	v_sub_f32_e32 v64, v64, v3
	v_sub_f32_e32 v65, v65, v3
	v_sub_f32_e32 v66, v66, v3
	v_sub_f32_e32 v67, v67, v3
	v_sub_f32_e32 v84, v84, v3
	v_sub_f32_e32 v85, v85, v3
	v_sub_f32_e32 v86, v86, v3
	v_sub_f32_e32 v87, v87, v3
	v_pk_mul_f32 v[198:199], v[198:199], v[200:201]
	ds_read_b64_tr_b16 v[124:125], v215 offset:53248
	ds_read_b64_tr_b16 v[100:101], v215 offset:53280
	ds_read_b64_tr_b16 v[116:117], v215 offset:53312
	ds_read_b64_tr_b16 v[96:97], v215 offset:53344
	ds_read_b64_tr_b16 v[126:127], v215 offset:57856
	ds_read_b64_tr_b16 v[102:103], v215 offset:57888
	ds_read_b64_tr_b16 v[118:119], v215 offset:57920
	ds_read_b64_tr_b16 v[98:99], v215 offset:57952
